# v24 + grid barrier L1 invalidate issued by wave0 at barrier entry (overlapped with store drain) instead of after release
# speedup vs baseline: 1.0422x; 1.0194x over previous
; __device__ __forceinline__ unsigned xb_add(unsigned* p, unsigned v) { return __hip_atomic_fetch_add(p, v, __ATOMIC_RELAXED, __HIP_MEMORY_SCOPE_AGENT); }
; __device__ __forceinline__ void xcd_barrier(const XcdBarrier& b) {
;     ...
;             __builtin_amdgcn_fence(__ATOMIC_ACQUIRE, "agent");
;             xb_add(&bar[XB_XGEN(b.x)], 1u);
.LBB0_152:
	s_or_b64 exec, exec, s[4:5]
	s_mov_b64 s[4:5], exec
	v_mbcnt_lo_u32_b32 v0, s4, 0
	v_mbcnt_hi_u32_b32 v0, s5, v0
	v_cmp_eq_u32_e32 vcc, 0, v0
	s_waitcnt vmcnt(0) lgkmcnt(0)
	s_and_saveexec_b64 s[10:11], vcc
	s_cbranch_execz .LBB0_154
	s_bcnt1_i32_b64 s0, s[4:5]
	v_mov_b32_e32 v0, 0x2000
	v_mov_b32_e32 v1, s0
	global_atomic_add v0, v1, s[6:7] offset:1024

; __device__ __forceinline__ unsigned xb_add(unsigned* p, unsigned v) { return __hip_atomic_fetch_add(p, v, __ATOMIC_RELAXED, __HIP_MEMORY_SCOPE_AGENT); }
; __device__ __forceinline__ void xcd_barrier(const XcdBarrier& b) {
;     ...
;             __builtin_amdgcn_fence(__ATOMIC_ACQUIRE, "agent");
;             xb_add(&bar[XB_XGEN(b.x)], 1u);
.LBB0_235:
	s_or_b64 exec, exec, s[4:5]
	s_mov_b64 s[4:5], exec
	v_mbcnt_lo_u32_b32 v2, s4, 0
	v_mbcnt_hi_u32_b32 v2, s5, v2
	v_cmp_eq_u32_e32 vcc, 0, v2
	s_waitcnt vmcnt(0)
	s_and_saveexec_b64 s[10:11], vcc
	s_cbranch_execz .LBB0_237
	s_bcnt1_i32_b64 s4, s[4:5]
	v_mov_b32_e32 v2, s4
	v_mov_b32_e32 v3, 0x2000
	global_atomic_add v3, v2, s[6:7] offset:1024

; __device__ __forceinline__ unsigned xb_add(unsigned* p, unsigned v) { return __hip_atomic_fetch_add(p, v, __ATOMIC_RELAXED, __HIP_MEMORY_SCOPE_AGENT); }
; __device__ __forceinline__ void xcd_barrier(const XcdBarrier& b) {
;     ...
;             __builtin_amdgcn_fence(__ATOMIC_ACQUIRE, "agent");
;             xb_add(&bar[XB_XGEN(b.x)], 1u);
.LBB0_454:
	s_or_b64 exec, exec, s[4:5]
	s_mov_b64 s[4:5], exec
	v_mbcnt_lo_u32_b32 v2, s4, 0
	v_mbcnt_hi_u32_b32 v2, s5, v2
	v_cmp_eq_u32_e32 vcc, 0, v2
	s_waitcnt vmcnt(0)
	s_and_saveexec_b64 s[8:9], vcc
	s_cbranch_execz .LBB0_456
	s_bcnt1_i32_b64 s4, s[4:5]
	v_mov_b32_e32 v2, s4
	v_mov_b32_e32 v3, 0x2000
	global_atomic_add v3, v2, s[6:7] offset:1024
